# v19 plus: the 12-register refinement loop counts on the VALU too (one DPP reduction per bit)
# baseline (speedup 1.0000x reference)
.LBB0_1857:
	v_lshl_or_b32 v161, 1, v160, v134
	s_waitcnt lgkmcnt(0)
	v_mov_b32_e32 v204, 0
	v_cmp_ge_u32_e32 vcc, v159, v161
	v_cmp_ge_u32_e64 s[98:99], v156, v161
	v_cmp_ge_u32_e64 s[100:101], v155, v161
	v_addc_co_u32_e32 v204, vcc, 0, v204, vcc
	v_cmp_ge_u32_e32 vcc, v152, v161
	v_addc_co_u32_e64 v204, s[98:99], 0, v204, s[98:99]
	v_cmp_ge_u32_e64 s[98:99], v151, v161
	v_addc_co_u32_e64 v204, s[100:101], 0, v204, s[100:101]
	v_cmp_ge_u32_e64 s[100:101], v145, v161
	v_addc_co_u32_e32 v204, vcc, 0, v204, vcc
	v_cmp_ge_u32_e32 vcc, v144, v161
	v_addc_co_u32_e64 v204, s[98:99], 0, v204, s[98:99]
	v_cmp_ge_u32_e64 s[98:99], v141, v161
	v_addc_co_u32_e64 v204, s[100:101], 0, v204, s[100:101]
	v_cmp_ge_u32_e64 s[100:101], v140, v161
	v_addc_co_u32_e32 v204, vcc, 0, v204, vcc
	v_cmp_ge_u32_e32 vcc, v137, v161
	v_addc_co_u32_e64 v204, s[98:99], 0, v204, s[98:99]
	v_cmp_ge_u32_e64 s[98:99], v136, v161
	v_addc_co_u32_e64 v204, s[100:101], 0, v204, s[100:101]
	v_cmp_ge_u32_e64 s[100:101], v3, v161
	v_addc_co_u32_e32 v204, vcc, 0, v204, vcc
	s_nop 1
	v_addc_co_u32_e64 v204, s[98:99], 0, v204, s[98:99]
	v_addc_co_u32_e64 v204, s[100:101], 0, v204, s[100:101]
	s_nop 0
	s_nop 1
	v_add_u32_dpp v205, v204, v204 quad_perm:[1,0,3,2] row_mask:0xf bank_mask:0xf
	s_nop 1
	v_add_u32_dpp v205, v205, v205 quad_perm:[2,3,0,1] row_mask:0xf bank_mask:0xf
	s_nop 1
	v_add_u32_dpp v205, v205, v205 row_half_mirror row_mask:0xf bank_mask:0xf
	s_nop 1
	v_add_u32_dpp v205, v205, v205 row_mirror row_mask:0xf bank_mask:0xf
	s_nop 1
	v_readlane_b32 s98, v205, 0
	v_readlane_b32 s99, v205, 16
	v_readlane_b32 s100, v205, 32
	v_readlane_b32 s101, v205, 48
	s_add_i32 s98, s98, s99
	s_add_i32 s100, s100, s101
	s_add_i32 s4, s98, s100
	s_cmpk_gt_u32 s4, 0xff
	s_cselect_b64 vcc, -1, 0
	s_cmpk_eq_i32 s4, 0x100
	s_cselect_b64 s[30:31], -1, 0
	v_cndmask_b32_e32 v134, v134, v161, vcc
	v_subrev_co_u32_e32 v160, vcc, 1, v160
	s_or_b64 s[4:5], s[30:31], vcc
	s_or_b64 s[72:73], s[30:31], s[72:73]
	s_andn2_b64 vcc, exec, s[4:5]
	s_cbranch_vccnz .LBB0_1857
	s_branch .LBB0_1859

.LBB0_4116:
	v_lshl_or_b32 v161, 1, v160, v134
	s_waitcnt lgkmcnt(0)
	v_mov_b32_e32 v204, 0
	v_cmp_ge_u32_e32 vcc, v159, v161
	v_cmp_ge_u32_e64 s[98:99], v156, v161
	v_cmp_ge_u32_e64 s[100:101], v155, v161
	v_addc_co_u32_e32 v204, vcc, 0, v204, vcc
	v_cmp_ge_u32_e32 vcc, v152, v161
	v_addc_co_u32_e64 v204, s[98:99], 0, v204, s[98:99]
	v_cmp_ge_u32_e64 s[98:99], v151, v161
	v_addc_co_u32_e64 v204, s[100:101], 0, v204, s[100:101]
	v_cmp_ge_u32_e64 s[100:101], v145, v161
	v_addc_co_u32_e32 v204, vcc, 0, v204, vcc
	v_cmp_ge_u32_e32 vcc, v144, v161
	v_addc_co_u32_e64 v204, s[98:99], 0, v204, s[98:99]
	v_cmp_ge_u32_e64 s[98:99], v141, v161
	v_addc_co_u32_e64 v204, s[100:101], 0, v204, s[100:101]
	v_cmp_ge_u32_e64 s[100:101], v140, v161
	v_addc_co_u32_e32 v204, vcc, 0, v204, vcc
	v_cmp_ge_u32_e32 vcc, v137, v161
	v_addc_co_u32_e64 v204, s[98:99], 0, v204, s[98:99]
	v_cmp_ge_u32_e64 s[98:99], v136, v161
	v_addc_co_u32_e64 v204, s[100:101], 0, v204, s[100:101]
	v_cmp_ge_u32_e64 s[100:101], v3, v161
	v_addc_co_u32_e32 v204, vcc, 0, v204, vcc
	s_nop 1
	v_addc_co_u32_e64 v204, s[98:99], 0, v204, s[98:99]
	v_addc_co_u32_e64 v204, s[100:101], 0, v204, s[100:101]
	s_nop 0
	s_nop 1
	v_add_u32_dpp v205, v204, v204 quad_perm:[1,0,3,2] row_mask:0xf bank_mask:0xf
	s_nop 1
	v_add_u32_dpp v205, v205, v205 quad_perm:[2,3,0,1] row_mask:0xf bank_mask:0xf
	s_nop 1
	v_add_u32_dpp v205, v205, v205 row_half_mirror row_mask:0xf bank_mask:0xf
	s_nop 1
	v_add_u32_dpp v205, v205, v205 row_mirror row_mask:0xf bank_mask:0xf
	s_nop 1
	v_readlane_b32 s98, v205, 0
	v_readlane_b32 s99, v205, 16
	v_readlane_b32 s100, v205, 32
	v_readlane_b32 s101, v205, 48
	s_add_i32 s98, s98, s99
	s_add_i32 s100, s100, s101
	s_add_i32 s4, s98, s100
	s_cmpk_gt_u32 s4, 0xff
	s_cselect_b64 vcc, -1, 0
	s_cmpk_eq_i32 s4, 0x100
	s_cselect_b64 s[30:31], -1, 0
	v_cndmask_b32_e32 v134, v134, v161, vcc
	v_subrev_co_u32_e32 v160, vcc, 1, v160
	s_or_b64 s[4:5], s[30:31], vcc
	s_or_b64 s[88:89], s[30:31], s[88:89]
	s_andn2_b64 vcc, exec, s[4:5]
	s_cbranch_vccnz .LBB0_4116
	s_branch .LBB0_4118
